# attention loop: SGPR-base LDS-DMA addressing (no 64-bit VALU), deferred address updates, XOR-toggled ring offsets, paired lgkmcnt waits
# speedup vs baseline: 1.0542x; 1.0056x over previous
; __device__ __forceinline__ void attn_unit(const Args& a, int l, int b, int h, int R0, bool special, LAS unsigned char* lds, float kb, int wv, bool pre, bool hasn, int nb, int nh, int nR0) {
;     ...
;     if (wave >= 4) __builtin_amdgcn_s_setprio(1);
.Lfa_entry:
	v_mov_b32_e32 v210, 0
	v_mov_b32_e32 v211, 0
	v_mov_b32_e32 v212, 0
	v_mov_b32_e32 v213, 0
	v_mov_b32_e32 v214, 0
	v_mov_b32_e32 v215, 0
	v_mov_b32_e32 v216, 0
	v_mov_b32_e32 v217, 0
	v_mov_b32_e32 v218, 0
	v_mov_b32_e32 v219, 0
	v_mov_b32_e32 v220, 0
	v_mov_b32_e32 v221, 0
	v_mov_b32_e32 v222, 0
	v_mov_b32_e32 v223, 0
	v_mov_b32_e32 v224, 0
	v_mov_b32_e32 v225, 0
	v_mov_b32_e32 v234, 0
	v_mov_b32_e32 v235, 0
	v_mov_b32_e32 v236, 0
	v_mov_b32_e32 v237, 0
	v_mov_b32_e32 v238, 0
	v_mov_b32_e32 v239, 0
	v_mov_b32_e32 v240, 0
	v_mov_b32_e32 v241, 0
	v_mov_b32_e32 v248, 0
	v_mov_b32_e32 v249, 0
	v_mov_b32_e32 v250, 0
	v_mov_b32_e32 v251, 0
	s_mov_b32 s0, 0xd000
	v_add3_u32 v247, v26, v28, s0
	v_readfirstlane_b32 s22, v20
	v_readfirstlane_b32 s23, v21
	s_nop 1
	v_subrev_u32_e32 v0, s22, v20
	v_subrev_u32_e32 v14, s22, v18
	s_add_u32 s22, s22, 0x220c000
	s_addc_u32 s23, s23, 0
	v_readfirstlane_b32 s34, v22
	v_readfirstlane_b32 s35, v23
	s_nop 1
	v_subrev_u32_e32 v15, s34, v22
	v_subrev_u32_e32 v197, s34, v24
	s_add_u32 s34, s34, 0x1b900180
	s_addc_u32 s35, s35, 0
	s_and_b32 s88, s87, 3
	s_mulk_i32 s88, 0x3400
	s_add_i32 s90, s87, 1
	s_and_b32 s90, s90, 3
	s_mulk_i32 s90, 0x3400
	s_mov_b32 s32, 0
	s_movk_i32 s30, 0x2400
	s_mov_b32 s31, 0
.Lfa_loop:
	s_add_i32 s76, s87, 2
	v_add_u32_e32 v230, s88, v190
	v_add_u32_e32 v231, s30, v247
	ds_read_b128 v[2:5], v230
	ds_read_b128 v[6:9], v230 offset:6656
	ds_read_b128 v[10:13], v230 offset:32
	ds_read_b128 v[198:201], v230 offset:6688
	ds_read_b128 v[202:205], v230 offset:64
	ds_read_b128 v[206:209], v230 offset:6720
	v_mfma_f32_32x32x16_bf16 v[64:79], v[210:213], v[234:237], v[64:79]
	v_exp_f32_e32 v96, v96
	v_exp_f32_e32 v97, v97
	v_add_f32_e32 v248, v248, v96
	v_exp_f32_e32 v98, v98
	v_mfma_f32_32x32x16_bf16 v[48:63], v[214:217], v[234:237], v[48:63]
	s_mov_b32 s96, 0
	s_cmp_gt_u32 s76, s73
	s_cbranch_scc1 .Lfa_a_nok
	s_xor_b32 s1, s88, 0x6800
	s_add_i32 m0, s1, s66
	s_mov_b32 s96, s75
	global_load_lds_dwordx4 v0, s[22:23]
	s_and_b64 vcc, exec, s[40:41]
	s_cbranch_vccnz .Lfa_a_nok
	s_add_i32 m0, s1, s78
	s_and_b64 vcc, exec, s[42:43]
	global_load_lds_dwordx4 v14, s[22:23]
.Lfa_a_nok:
	s_add_u32 s22, s22, 0x3000
	s_addc_u32 s23, s23, 0
	v_add_f32_e32 v249, v249, v97
	v_exp_f32_e32 v99, v99
	v_add_f32_e32 v250, v250, v98
	v_exp_f32_e32 v100, v100
	v_mfma_f32_32x32x16_bf16 v[64:79], v[218:221], v[238:241], v[64:79]
	ds_read_b128 v[210:213], v230 offset:96
	ds_read_b128 v[214:217], v230 offset:6752
	v_add_f32_e32 v251, v251, v99
	v_exp_f32_e32 v101, v101
	v_add_f32_e32 v248, v248, v100
	v_exp_f32_e32 v102, v102
	v_mfma_f32_32x32x16_bf16 v[48:63], v[222:225], v[238:241], v[48:63]
	ds_read_b128 v[218:221], v230 offset:128
	ds_read_b128 v[222:225], v230 offset:6784
	ds_read_b128 v[234:237], v230 offset:160
	ds_read_b128 v[238:241], v230 offset:6816
	s_add_i32 s1, s87, 1
	s_cmp_gt_u32 s1, s73
	s_cbranch_scc1 .Lfa_a_nov
	s_add_i32 s1, s31, s66
	s_add_i32 m0, s1, 0xd000
	s_and_b64 vcc, exec, s[42:43]
	global_load_lds_dwordx4 v15, s[34:35]
	s_cbranch_vccnz .Lfa_a_nov
	s_add_i32 m0, s31, 0xf000
	s_nop 0
	global_load_lds_dwordx4 v197, s[34:35]
.Lfa_a_nov:
	s_add_u32 s34, s34, 0x80
	s_addc_u32 s35, s35, 0
	v_add_f32_e32 v249, v249, v101
	v_exp_f32_e32 v103, v103
	v_add_f32_e32 v250, v250, v102
	v_add_f32_e32 v251, v251, v103
	s_waitcnt lgkmcnt(10)
	v_mfma_f32_32x32x16_bf16 v[128:143], v[2:5], v[156:159], v[32:47]
	v_cvt_pk_bf16_f32 v96, v96, v97
	v_cvt_pk_bf16_f32 v97, v98, v99
	v_cvt_pk_bf16_f32 v98, v100, v101
	v_cvt_pk_bf16_f32 v99, v102, v103
	v_mfma_f32_32x32x16_bf16 v[112:127], v[6:9], v[156:159], v[32:47]
	ds_read_b128 v[2:5], v231
	ds_read_b128 v[6:9], v231 offset:4608
	v_exp_f32_e32 v104, v104
	v_exp_f32_e32 v105, v105
	v_add_f32_e32 v248, v248, v104
	v_exp_f32_e32 v106, v106
	s_waitcnt lgkmcnt(10)
	v_mfma_f32_32x32x16_bf16 v[128:143], v[10:13], v[160:163], v[128:143]
	v_add_f32_e32 v249, v249, v105
	v_exp_f32_e32 v107, v107
	v_add_f32_e32 v250, v250, v106
	v_exp_f32_e32 v108, v108
	v_mfma_f32_32x32x16_bf16 v[112:127], v[198:201], v[160:163], v[112:127]
	ds_read_b128 v[10:13], v231 offset:32
	ds_read_b128 v[198:201], v231 offset:4640
	v_add_f32_e32 v251, v251, v107
	v_exp_f32_e32 v109, v109
	v_add_f32_e32 v248, v248, v108
	v_exp_f32_e32 v110, v110
	s_waitcnt lgkmcnt(10)
	v_mfma_f32_32x32x16_bf16 v[128:143], v[202:205], v[164:167], v[128:143]
	v_add_f32_e32 v249, v249, v109
	v_exp_f32_e32 v111, v111
	v_add_f32_e32 v250, v250, v110
	v_add_f32_e32 v251, v251, v111
	v_mfma_f32_32x32x16_bf16 v[112:127], v[206:209], v[164:167], v[112:127]
	v_cvt_pk_bf16_f32 v104, v104, v105
	v_cvt_pk_bf16_f32 v105, v106, v107
	v_cvt_pk_bf16_f32 v106, v108, v109
	v_cvt_pk_bf16_f32 v107, v110, v111
	s_waitcnt lgkmcnt(8)
	v_mfma_f32_32x32x16_bf16 v[128:143], v[210:213], v[144:147], v[128:143]
	v_exp_f32_e32 v80, v80
	v_exp_f32_e32 v81, v81
	v_add_f32_e32 v248, v248, v80
	v_exp_f32_e32 v82, v82
	v_mfma_f32_32x32x16_bf16 v[112:127], v[214:217], v[144:147], v[112:127]
	ds_read_b128 v[210:213], v231 offset:64
	ds_read_b128 v[214:217], v231 offset:4672
	v_add_f32_e32 v249, v249, v81
	v_exp_f32_e32 v83, v83
	v_add_f32_e32 v250, v250, v82
	v_exp_f32_e32 v84, v84
	s_waitcnt lgkmcnt(8)
	v_mfma_f32_32x32x16_bf16 v[128:143], v[218:221], v[148:151], v[128:143]
	v_add_f32_e32 v251, v251, v83
	v_exp_f32_e32 v85, v85
	v_add_f32_e32 v248, v248, v84
	v_exp_f32_e32 v86, v86
	v_mfma_f32_32x32x16_bf16 v[112:127], v[222:225], v[148:151], v[112:127]
	ds_read_b128 v[218:221], v231 offset:96
	ds_read_b128 v[222:225], v231 offset:4704
	v_add_f32_e32 v249, v249, v85
	v_exp_f32_e32 v87, v87
	v_add_f32_e32 v250, v250, v86
	v_add_f32_e32 v251, v251, v87
	s_waitcnt lgkmcnt(8)
	v_mfma_f32_32x32x16_bf16 v[128:143], v[234:237], v[152:155], v[128:143]
	v_exp_f32_e32 v88, v88
	v_exp_f32_e32 v89, v89
	v_add_f32_e32 v248, v248, v88
	v_exp_f32_e32 v90, v90
	v_mfma_f32_32x32x16_bf16 v[112:127], v[238:241], v[152:155], v[112:127]
	v_add_f32_e32 v249, v249, v89
	v_exp_f32_e32 v91, v91
	v_add_f32_e32 v250, v250, v90
	v_exp_f32_e32 v92, v92
	s_waitcnt lgkmcnt(6)
	v_mfma_f32_32x32x16_bf16 v[64:79], v[2:5], v[96:99], v[64:79]
	v_add_f32_e32 v251, v251, v91
	v_exp_f32_e32 v93, v93
	v_add_f32_e32 v248, v248, v92
	v_exp_f32_e32 v94, v94
	v_mfma_f32_32x32x16_bf16 v[48:63], v[6:9], v[96:99], v[48:63]
	v_add_f32_e32 v249, v249, v93
	v_exp_f32_e32 v95, v95
	v_add_f32_e32 v250, v250, v94
	v_add_f32_e32 v251, v251, v95
	s_waitcnt lgkmcnt(4)
	v_mfma_f32_32x32x16_bf16 v[64:79], v[10:13], v[104:107], v[64:79]
	v_cvt_pk_bf16_f32 v234, v80, v81
	v_cvt_pk_bf16_f32 v235, v82, v83
	v_cvt_pk_bf16_f32 v236, v84, v85
	v_cvt_pk_bf16_f32 v237, v86, v87
	v_mfma_f32_32x32x16_bf16 v[48:63], v[198:201], v[104:107], v[48:63]
	v_cvt_pk_bf16_f32 v238, v88, v89
	v_cvt_pk_bf16_f32 v239, v90, v91
	v_cvt_pk_bf16_f32 v240, v92, v93
	v_cvt_pk_bf16_f32 v241, v94, v95
	s_mov_b32 s1, s30
	s_add_i32 s30, s30, 0x2400
	s_cmp_eq_u32 s30, 0x6c00
	s_cselect_b32 s30, 0, s30
	s_mov_b32 s31, s1
	s_sub_i32 s0, s84, 64
	s_cmp_le_i32 s0, s74
	s_cbranch_scc0 .Lfa_mask_a

.Lfa_a_wj:
	s_waitcnt lgkmcnt(0)
	s_barrier
	v_add_u32_e32 v230, s90, v190
	v_add_u32_e32 v231, s30, v247
	ds_read_b128 v[2:5], v230
	ds_read_b128 v[6:9], v230 offset:6656
	ds_read_b128 v[10:13], v230 offset:32
	ds_read_b128 v[198:201], v230 offset:6688
	ds_read_b128 v[202:205], v230 offset:64
	ds_read_b128 v[206:209], v230 offset:6720
	v_mfma_f32_32x32x16_bf16 v[64:79], v[210:213], v[234:237], v[64:79]
	v_exp_f32_e32 v128, v128
	v_exp_f32_e32 v129, v129
	v_add_f32_e32 v248, v248, v128
	v_exp_f32_e32 v130, v130
	v_mfma_f32_32x32x16_bf16 v[48:63], v[214:217], v[234:237], v[48:63]
	s_mov_b32 s96, 0
	s_add_i32 s1, s76, 1
	s_cmp_gt_u32 s1, s73
	s_cbranch_scc1 .Lfa_b_nok
	s_xor_b32 s1, s90, 0xa800
	s_add_i32 m0, s1, s66
	s_mov_b32 s96, s75
	global_load_lds_dwordx4 v0, s[22:23]
	s_and_b64 vcc, exec, s[40:41]
	s_cbranch_vccnz .Lfa_b_nok
	s_add_i32 m0, s1, s78
	s_and_b64 vcc, exec, s[42:43]
	global_load_lds_dwordx4 v14, s[22:23]
.Lfa_b_nok:
	s_add_u32 s22, s22, 0x3000
	s_addc_u32 s23, s23, 0
	v_add_f32_e32 v249, v249, v129
	v_exp_f32_e32 v131, v131
	v_add_f32_e32 v250, v250, v130
	v_exp_f32_e32 v132, v132
	v_mfma_f32_32x32x16_bf16 v[64:79], v[218:221], v[238:241], v[64:79]
	ds_read_b128 v[210:213], v230 offset:96
	ds_read_b128 v[214:217], v230 offset:6752
	v_add_f32_e32 v251, v251, v131
	v_exp_f32_e32 v133, v133
	v_add_f32_e32 v248, v248, v132
	v_exp_f32_e32 v134, v134
	v_mfma_f32_32x32x16_bf16 v[48:63], v[222:225], v[238:241], v[48:63]
	ds_read_b128 v[218:221], v230 offset:128
	ds_read_b128 v[222:225], v230 offset:6784
	ds_read_b128 v[234:237], v230 offset:160
	ds_read_b128 v[238:241], v230 offset:6816
	s_cmp_gt_u32 s76, s73
	s_cbranch_scc1 .Lfa_b_nov
	s_add_i32 s1, s31, s66
	s_add_i32 m0, s1, 0xd000
	s_and_b64 vcc, exec, s[42:43]
	global_load_lds_dwordx4 v15, s[34:35]
	s_cbranch_vccnz .Lfa_b_nov
	s_add_i32 m0, s31, 0xf000
	s_nop 0
	global_load_lds_dwordx4 v197, s[34:35]
.Lfa_b_nov:
	s_add_u32 s34, s34, 0x80
	s_addc_u32 s35, s35, 0
	v_add_f32_e32 v249, v249, v133
	v_exp_f32_e32 v135, v135
	v_add_f32_e32 v250, v250, v134
	v_add_f32_e32 v251, v251, v135
	s_waitcnt lgkmcnt(10)
	v_mfma_f32_32x32x16_bf16 v[96:111], v[2:5], v[156:159], v[32:47]
	v_cvt_pk_bf16_f32 v128, v128, v129
	v_cvt_pk_bf16_f32 v129, v130, v131
	v_cvt_pk_bf16_f32 v130, v132, v133
	v_cvt_pk_bf16_f32 v131, v134, v135
	v_mfma_f32_32x32x16_bf16 v[80:95], v[6:9], v[156:159], v[32:47]
	ds_read_b128 v[2:5], v231
	ds_read_b128 v[6:9], v231 offset:4608
	v_exp_f32_e32 v136, v136
	v_exp_f32_e32 v137, v137
	v_add_f32_e32 v248, v248, v136
	v_exp_f32_e32 v138, v138
	s_waitcnt lgkmcnt(10)
	v_mfma_f32_32x32x16_bf16 v[96:111], v[10:13], v[160:163], v[96:111]
	v_add_f32_e32 v249, v249, v137
	v_exp_f32_e32 v139, v139
	v_add_f32_e32 v250, v250, v138
	v_exp_f32_e32 v140, v140
	v_mfma_f32_32x32x16_bf16 v[80:95], v[198:201], v[160:163], v[80:95]
	ds_read_b128 v[10:13], v231 offset:32
	ds_read_b128 v[198:201], v231 offset:4640
	v_add_f32_e32 v251, v251, v139
	v_exp_f32_e32 v141, v141
	v_add_f32_e32 v248, v248, v140
	v_exp_f32_e32 v142, v142
	s_waitcnt lgkmcnt(10)
	v_mfma_f32_32x32x16_bf16 v[96:111], v[202:205], v[164:167], v[96:111]
	v_add_f32_e32 v249, v249, v141
	v_exp_f32_e32 v143, v143
	v_add_f32_e32 v250, v250, v142
	v_add_f32_e32 v251, v251, v143
	v_mfma_f32_32x32x16_bf16 v[80:95], v[206:209], v[164:167], v[80:95]
	v_cvt_pk_bf16_f32 v136, v136, v137
	v_cvt_pk_bf16_f32 v137, v138, v139
	v_cvt_pk_bf16_f32 v138, v140, v141
	v_cvt_pk_bf16_f32 v139, v142, v143
	s_waitcnt lgkmcnt(8)
	v_mfma_f32_32x32x16_bf16 v[96:111], v[210:213], v[144:147], v[96:111]
	v_exp_f32_e32 v112, v112
	v_exp_f32_e32 v113, v113
	v_add_f32_e32 v248, v248, v112
	v_exp_f32_e32 v114, v114
	v_mfma_f32_32x32x16_bf16 v[80:95], v[214:217], v[144:147], v[80:95]
	ds_read_b128 v[210:213], v231 offset:64
	ds_read_b128 v[214:217], v231 offset:4672
	v_add_f32_e32 v249, v249, v113
	v_exp_f32_e32 v115, v115
	v_add_f32_e32 v250, v250, v114
	v_exp_f32_e32 v116, v116
	s_waitcnt lgkmcnt(8)
	v_mfma_f32_32x32x16_bf16 v[96:111], v[218:221], v[148:151], v[96:111]
	v_add_f32_e32 v251, v251, v115
	v_exp_f32_e32 v117, v117
	v_add_f32_e32 v248, v248, v116
	v_exp_f32_e32 v118, v118
	v_mfma_f32_32x32x16_bf16 v[80:95], v[222:225], v[148:151], v[80:95]
	ds_read_b128 v[218:221], v231 offset:96
	ds_read_b128 v[222:225], v231 offset:4704
	v_add_f32_e32 v249, v249, v117
	v_exp_f32_e32 v119, v119
	v_add_f32_e32 v250, v250, v118
	v_add_f32_e32 v251, v251, v119
	s_waitcnt lgkmcnt(8)
	v_mfma_f32_32x32x16_bf16 v[96:111], v[234:237], v[152:155], v[96:111]
	v_exp_f32_e32 v120, v120
	v_exp_f32_e32 v121, v121
	v_add_f32_e32 v248, v248, v120
	v_exp_f32_e32 v122, v122
	v_mfma_f32_32x32x16_bf16 v[80:95], v[238:241], v[152:155], v[80:95]
	v_add_f32_e32 v249, v249, v121
	v_exp_f32_e32 v123, v123
	v_add_f32_e32 v250, v250, v122
	v_exp_f32_e32 v124, v124
	s_waitcnt lgkmcnt(6)
	v_mfma_f32_32x32x16_bf16 v[64:79], v[2:5], v[128:131], v[64:79]
	v_add_f32_e32 v251, v251, v123
	v_exp_f32_e32 v125, v125
	v_add_f32_e32 v248, v248, v124
	v_exp_f32_e32 v126, v126
	v_mfma_f32_32x32x16_bf16 v[48:63], v[6:9], v[128:131], v[48:63]
	v_add_f32_e32 v249, v249, v125
	v_exp_f32_e32 v127, v127
	v_add_f32_e32 v250, v250, v126
	v_add_f32_e32 v251, v251, v127
	s_waitcnt lgkmcnt(4)
	v_mfma_f32_32x32x16_bf16 v[64:79], v[10:13], v[136:139], v[64:79]
	v_cvt_pk_bf16_f32 v234, v112, v113
	v_cvt_pk_bf16_f32 v235, v114, v115
	v_cvt_pk_bf16_f32 v236, v116, v117
	v_cvt_pk_bf16_f32 v237, v118, v119
	v_mfma_f32_32x32x16_bf16 v[48:63], v[198:201], v[136:139], v[48:63]
	v_cvt_pk_bf16_f32 v238, v120, v121
	v_cvt_pk_bf16_f32 v239, v122, v123
	v_cvt_pk_bf16_f32 v240, v124, v125
	v_cvt_pk_bf16_f32 v241, v126, v127
	s_mov_b32 s1, s30
	s_add_i32 s30, s30, 0x2400
	s_cmp_eq_u32 s30, 0x6c00
	s_cselect_b32 s30, 0, s30
	s_mov_b32 s31, s1
	s_cmp_le_i32 s84, s74
	s_cbranch_scc0 .Lfa_mask_b

; #define ATT_ISSUE(t) do { if ((t) + 3 <= TL) ATT_DMAK((t) + 3); if ((t) + 2 <= TL) ATT_DMAV((t) + 2); } while (0)
; #define ATT_SYNC(t) do { if ((t) + 3 <= TL) { if (nis == 4) asm volatile("s_waitcnt vmcnt(4)" ::: "memory"); else if (nis == 3) asm volatile("s_waitcnt vmcnt(3)" ::: "memory"); else asm volatile("s_waitcnt vmcnt(2)" ::: "memory"); } \
;         else asm volatile("s_waitcnt vmcnt(0)" ::: "memory"); \
;         LDS_WAIT(); __builtin_amdgcn_s_barrier(); asm volatile("" ::: "memory"); } while (0)
; #define ATT_TAIL(t, C0, C1) do { ATT_ISSUE(t); bf16x8 vf[8], pa[4]; ATT_LDV(t); ATT_EXPP(C0, C1); ATT_PV(); ATT_SYNC(t); } while (0)
; __device__ __forceinline__ void attn_unit(const Args& a, int l, int b, int h, int R0, bool special, LAS unsigned char* lds, float kb, int wv, bool pre, bool hasn, int nb, int nh, int nR0) {
;     ...
;         f32x16 pb0, pb1; int t = 1;
;         for (; t + 1 < tw; t += 2) { ATT_BODY(t, pc0, pc1, pb0, pb1); ATT_BODY(t + 1, pb0, pb1, pc0, pc1); }
;         if (t < tw) { ATT_BODY(t, pc0, pc1, pb0, pb1); ++t; ATT_TAIL(t, pb0, pb1); ++t; }
;         else if (t == tw) { ATT_TAIL(t, pc0, pc1); ++t; }
;         for (; t <= TL; ++t) { ATT_ISSUE(t); ATT_SYNC(t); }
;     }
;     __builtin_amdgcn_s_setprio(0);
.Lfa_b_wj:
	s_waitcnt lgkmcnt(0)
	s_barrier
	s_addk_i32 s83, 0x4800
	s_addk_i32 s84, 0x80
	s_addk_i32 s85, 0x4800
	s_add_i32 s79, s79, 2
	s_add_i32 s86, s86, 2
	s_add_i32 s80, s80, 2
	s_add_i32 s32, s32, 1
	s_xor_b32 s88, s88, 0x6800
	s_xor_b32 s90, s90, 0xa800
	s_cmp_lt_i32 s76, s77
	s_cbranch_scc0 .Lfa_exit
	s_mov_b32 s87, s76
	s_branch .Lfa_loop
.Lfa_exit:
	s_mul_i32 s0, s32, 0x6000
	s_mov_b32 s1, 0
	v_lshl_add_u64 v[18:19], v[18:19], 0, s[0:1]
	v_lshl_add_u64 v[20:21], v[20:21], 0, s[0:1]
	s_lshl_b32 s0, s32, 8
	v_lshl_add_u64 v[22:23], v[22:23], 0, s[0:1]
	v_lshl_add_u64 v[24:25], v[24:25], 0, s[0:1]
	v_mfma_f32_32x32x16_bf16 v[64:79], v[210:213], v[234:237], v[64:79]
	v_mfma_f32_32x32x16_bf16 v[48:63], v[214:217], v[234:237], v[48:63]
	v_mfma_f32_32x32x16_bf16 v[64:79], v[218:221], v[238:241], v[64:79]
	v_mfma_f32_32x32x16_bf16 v[48:63], v[222:225], v[238:241], v[48:63]
	v_add_f32_e32 v248, v248, v249
	v_add_f32_e32 v250, v250, v251
	v_add_f32_e32 v248, v248, v250
	v_add_f32_e32 v27, v27, v248
	s_nop 7
	s_nop 7
	s_branch .LBB0_112
